# speedup vs baseline: 1.0074x; 1.0012x over previous
; #define LAS __attribute__((address_space(3)))
; __device__ __forceinline__ void p0_transpose_item(const float* W, int K, int N, const float* gain, const float* gain2  , bf16_t* WT, LAS unsigned* scr, int item, int lane) {
;     const int nblk = N / 64, kb = item / nblk, nb = item % nblk, k0 = 64 * kb, n0 = 64 * nb;
;     if (gain2 && k0 >= 1024) gain = gain2 - 1024;
;     const int n4 = lane & 15, kq = lane >> 4;
;     f32x4 r0[8], r1[8];
;     const float* src = W + (size_t)(k0 + 2 * kq) * N + n0 + 4 * n4;
; #pragma unroll
;     for (int j = 0; j < 8; ++j) { r0[j] = __builtin_nontemporal_load((const f32x4*)(src + (size_t)(8 * j) * N)); r1[j] = __builtin_nontemporal_load((const f32x4*)(src + (size_t)(8 * j + 1) * N)); }
; #pragma unroll
;     for (int j = 0; j < 8; ++j) {
;         float g0 = 1.f, g1 = 1.f; if (gain) { g0 = gain[k0 + 8 * j + 2 * kq]; g1 = gain[k0 + 8 * j + 2 * kq + 1]; }
; __device__ __forceinline__ void p0_prologue(const Params& p, LAS unsigned char* lds, int tid) {
;     ...
;         p0_transpose_item(p.in[19] + (size_t)l * DM * DM, DM, DM, p.in[17] + l * 1024, p.in[18] + l * 1024, (bf16_t*)(wl + LO_WOUT), scr, r, lane);
.Lmy_w118:
	s_mov_b32 s0, 0x30c30c31
	v_mul_hi_i32 v26, v90, s0
	v_lshrrev_b32_e32 v27, 31, v26
	v_ashrrev_i32_e32 v26, 11, v26
	v_add_u32_e32 v100, v26, v27
	s_mov_b32 s0, 0x6400000
	v_mul_i32_i24_e32 v27, 0x2a00, v100
	v_mad_i64_i32 v[98:99], s[0:1], v100, s0, v[96:97]
	v_sub_u32_e32 v26, v90, v27
	s_movk_i32 s0, 0x4ff
	v_ashrrev_i32_e32 v101, 31, v100
	v_cmp_lt_i32_e32 vcc, s0, v26
	s_and_saveexec_b64 s[0:1], vcc
	s_xor_b64 s[26:27], exec, s[0:1]
	s_cbranch_execz .Lmy_w164
	s_movk_i32 s0, 0x14ff
	v_cmp_lt_u32_e32 vcc, s0, v26
	s_and_saveexec_b64 s[0:1], vcc
	s_xor_b64 s[0:1], exec, s[0:1]
	s_cbranch_execz .Lmy_w145
	s_movk_i32 s28, 0x24ff
	v_cmp_lt_u32_e32 vcc, s28, v26
	s_and_saveexec_b64 s[28:29], vcc
	s_xor_b64 s[28:29], exec, s[28:29]
	s_cbranch_execz .Lmy_w142
	s_movk_i32 s30, 0x25ff
	v_cmp_lt_u32_e32 vcc, s30, v26
	s_and_saveexec_b64 s[30:31], vcc
	s_xor_b64 s[30:31], exec, s[30:31]
	s_cbranch_execz .Lmy_w139
	v_add_u16_e32 v104, 0xda00, v26
	v_lshrrev_b16_e32 v26, 5, v104
	v_readlane_b32 s40, v253, 18
	v_lshlrev_b32_e32 v109, 6, v26
	v_lshlrev_b32_e32 v26, 6, v27
	v_lshlrev_b64 v[28:29], 24, v[100:101]
	v_readlane_b32 s46, v253, 24
	v_readlane_b32 s47, v253, 25
	v_sub_u32_e32 v26, v134, v26
	v_or_b32_e32 v105, v109, v91
	v_lshl_add_u64 v[28:29], s[46:47], 0, v[28:29]
	v_and_b32_e32 v108, 0x7c0, v26
	v_lshlrev_b32_e32 v26, 13, v105
	v_mov_b32_e32 v27, v93
	v_lshl_add_u64 v[26:27], v[28:29], 0, v[26:27]
	v_lshlrev_b32_e32 v28, 2, v108
	v_mov_b32_e32 v29, v93
	v_lshl_add_u64 v[26:27], v[26:27], 0, v[28:29]
	v_lshl_add_u64 v[26:27], v[26:27], 0, v[92:93]
	v_add_co_u32_e32 v28, vcc, s37, v26
	v_lshlrev_b32_e32 v100, 10, v100
	s_nop 0
	v_addc_co_u32_e32 v29, vcc, 0, v27, vcc
	global_load_dwordx4 v[82:85], v[26:27], off nt
	global_load_dwordx4 v[86:89], v[28:29], off nt
	v_add_co_u32_e32 v28, vcc, s38, v26
	v_ashrrev_i32_e32 v101, 31, v100
	s_nop 0
	v_addc_co_u32_e32 v29, vcc, 0, v27, vcc
	v_add_co_u32_e32 v30, vcc, s39, v26
	v_readlane_b32 s42, v253, 20
	s_nop 0
	v_addc_co_u32_e32 v31, vcc, 0, v27, vcc
	global_load_dwordx4 v[74:77], v[28:29], off nt
	global_load_dwordx4 v[78:81], v[30:31], off nt
	v_add_co_u32_e32 v28, vcc, s2, v26
	v_readlane_b32 s43, v253, 21
	s_nop 0
	v_addc_co_u32_e32 v29, vcc, 0, v27, vcc
	v_add_co_u32_e32 v30, vcc, s3, v26
	v_readlane_b32 s44, v253, 22
	s_nop 0
	v_addc_co_u32_e32 v31, vcc, 0, v27, vcc
	global_load_dwordx4 v[66:69], v[28:29], off nt
	global_load_dwordx4 v[70:73], v[30:31], off nt
	v_add_co_u32_e32 v28, vcc, s76, v26
	v_readlane_b32 s45, v253, 23
	s_nop 0
	v_addc_co_u32_e32 v29, vcc, 0, v27, vcc
	v_add_co_u32_e32 v30, vcc, s77, v26
	v_lshlrev_b64 v[100:101], 2, v[100:101]
	s_nop 0
	v_addc_co_u32_e32 v31, vcc, 0, v27, vcc
	global_load_dwordx4 v[58:61], v[28:29], off nt
	global_load_dwordx4 v[62:65], v[30:31], off nt
	v_add_co_u32_e32 v28, vcc, s78, v26
	s_movk_i32 s34, 0x1ff
	s_nop 0
	v_addc_co_u32_e32 v29, vcc, 0, v27, vcc
	v_add_co_u32_e32 v30, vcc, s79, v26
	v_lshl_add_u64 v[102:103], s[42:43], 0, v[100:101]
	s_nop 0
	v_addc_co_u32_e32 v31, vcc, 0, v27, vcc
	global_load_dwordx4 v[50:53], v[28:29], off nt
	s_waitcnt lgkmcnt(0)
	global_load_dwordx4 v[54:57], v[30:31], off nt
	v_add_co_u32_e32 v28, vcc, s80, v26
	v_lshl_add_u64 v[100:101], s[44:45], 0, v[100:101]
	s_nop 0
	v_addc_co_u32_e32 v29, vcc, 0, v27, vcc
	v_add_co_u32_e32 v30, vcc, s81, v26
	v_lshl_add_u64 v[100:101], v[100:101], 0, s[16:17]
	s_nop 0
	v_addc_co_u32_e32 v31, vcc, 0, v27, vcc
	global_load_dwordx4 v[42:45], v[28:29], off nt
	global_load_dwordx4 v[46:49], v[30:31], off nt
	v_add_co_u32_e32 v28, vcc, s82, v26
	v_mov_b32_e32 v106, 1.0
	s_nop 0
	v_addc_co_u32_e32 v29, vcc, 0, v27, vcc
	v_add_co_u32_e32 v30, vcc, s83, v26
	v_mov_b32_e32 v107, 1.0
	s_nop 0
	v_addc_co_u32_e32 v31, vcc, 0, v27, vcc
	global_load_dwordx4 v[34:37], v[28:29], off nt
	global_load_dwordx4 v[38:41], v[30:31], off nt
	v_add_co_u32_e32 v28, vcc, s84, v26
	v_readlane_b32 s41, v253, 19
	s_nop 0
	v_addc_co_u32_e32 v29, vcc, 0, v27, vcc
	v_add_co_u32_e32 v30, vcc, 0x72000, v26
	v_readlane_b32 s48, v253, 26
	s_nop 0
	v_addc_co_u32_e32 v31, vcc, 0, v27, vcc
	global_load_dwordx4 v[26:29], v[28:29], off nt
	s_nop 0
	global_load_dwordx4 v[30:33], v[30:31], off nt
	v_cmp_lt_u16_e32 vcc, s34, v104
	s_and_b64 vcc, s[6:7], vcc
	v_mov_b32_e32 v104, 1.0
	v_cndmask_b32_e32 v101, v103, v101, vcc
	v_cndmask_b32_e32 v100, v102, v100, vcc
	v_cmp_ne_u64_e32 vcc, 0, v[100:101]
	v_lshlrev_b32_e32 v102, 2, v105
	v_readlane_b32 s49, v253, 27
	v_readlane_b32 s50, v253, 28
	v_readlane_b32 s51, v253, 29
	v_readlane_b32 s52, v253, 30
	v_readlane_b32 s53, v253, 31
	v_readlane_b32 s54, v253, 32
	v_readlane_b32 s55, v253, 33
	s_and_saveexec_b64 s[34:35], vcc
	s_cbranch_execz .Lmy_w124
	v_mov_b32_e32 v103, v93
	v_lshl_add_u64 v[106:107], v[100:101], 0, v[102:103]
	global_load_dwordx2 v[182:183], v[106:107], off offset:32
	global_load_dwordx2 v[184:185], v[106:107], off offset:64
	global_load_dwordx2 v[186:187], v[106:107], off offset:96
	global_load_dwordx2 v[188:189], v[106:107], off offset:128
	global_load_dwordx2 v[190:191], v[106:107], off offset:160
	global_load_dwordx2 v[192:193], v[106:107], off offset:192
	global_load_dwordx2 v[194:195], v[106:107], off offset:224
	global_load_dwordx2 v[106:107], v[106:107], off
; __device__ __forceinline__ unsigned pk2(float lo, float hi) { unsigned r; asm volatile("v_cvt_pk_bf16_f32 %0, %1, %2" : "=v"(r) : "v"(lo), "v"(hi)); return r; }
; __device__ __forceinline__ void p0_transpose_item(const float* W, int K, int N, const float* gain, const float* gain2  , bf16_t* WT, LAS unsigned* scr, int item, int lane) {
;     ...
;     for (int j = 0; j < 8; ++j) {
;         float g0 = 1.f, g1 = 1.f; if (gain) { g0 = gain[k0 + 8 * j + 2 * kq]; g1 = gain[k0 + 8 * j + 2 * kq + 1]; }
; #pragma unroll
;         for (int i = 0; i < 4; ++i) scr[(4 * n4 + i) * 32 + (((j ^ (n4 & 7)) << 2) | kq)] = pk2(r0[j][i] * g0, r1[j][i] * g1);
;     }
.Lmy_w124:
	s_or_b64 exec, exec, s[34:35]
	s_waitcnt vmcnt(0)
	v_mul_f32_e32 v82, v82, v106
	v_mul_f32_e32 v86, v86, v107
	v_cvt_pk_bf16_f32 v82, v82, v86
	v_add_u32_e32 v86, v95, v110
	ds_write_b32 v86, v82
	v_mul_f32_e32 v82, v83, v106
	v_mul_f32_e32 v83, v87, v107
	v_cvt_pk_bf16_f32 v82, v82, v83
	ds_write_b32 v86, v82 offset:128
	v_mul_f32_e32 v82, v84, v106
	v_mul_f32_e32 v83, v88, v107
	v_cvt_pk_bf16_f32 v82, v82, v83
	ds_write_b32 v86, v82 offset:256
	v_mul_f32_e32 v82, v85, v106
	v_mov_b32_e32 v105, 1.0
	v_mul_f32_e32 v83, v89, v107
	v_cvt_pk_bf16_f32 v82, v82, v83
	ds_write_b32 v86, v82 offset:384
	s_and_saveexec_b64 s[34:35], vcc
	s_cbranch_execz .Lmy_w126
	v_mov_b32_e32 v103, v93
	v_lshl_add_u64 v[82:83], v[100:101], 0, v[102:103]
	v_mov_b32_e32 v104, v182
	v_mov_b32_e32 v105, v183
.Lmy_w126:
	s_or_b64 exec, exec, s[34:35]
	s_waitcnt vmcnt(0)
	v_mul_f32_e32 v74, v74, v104
	v_mul_f32_e32 v78, v78, v105
	v_cvt_pk_bf16_f32 v74, v74, v78
	v_add_u32_e32 v78, v111, v110
	ds_write_b32 v78, v74
	v_mul_f32_e32 v74, v75, v104
	v_mul_f32_e32 v75, v79, v105
	v_cvt_pk_bf16_f32 v74, v74, v75
	ds_write_b32 v78, v74 offset:128
	v_mul_f32_e32 v74, v76, v104
	v_mul_f32_e32 v75, v80, v105
	v_cvt_pk_bf16_f32 v74, v74, v75
	ds_write_b32 v78, v74 offset:256
	v_mul_f32_e32 v74, v77, v104
	v_mul_f32_e32 v75, v81, v105
	v_cvt_pk_bf16_f32 v74, v74, v75
	ds_write_b32 v78, v74 offset:384
	v_mov_b32_e32 v74, 1.0
	v_mov_b32_e32 v76, 1.0
	v_mov_b32_e32 v77, 1.0
	s_and_saveexec_b64 s[34:35], vcc
	s_cbranch_execz .Lmy_w128
	v_mov_b32_e32 v103, v93
	v_lshl_add_u64 v[76:77], v[100:101], 0, v[102:103]
	v_mov_b32_e32 v76, v184
	v_mov_b32_e32 v77, v185
.Lmy_w128:
	s_or_b64 exec, exec, s[34:35]
	s_waitcnt vmcnt(0)
	v_mul_f32_e32 v66, v66, v76
	v_mul_f32_e32 v70, v70, v77
	v_cvt_pk_bf16_f32 v66, v66, v70
	v_add_u32_e32 v70, v112, v110
	ds_write_b32 v70, v66
	v_mul_f32_e32 v66, v67, v76
	v_mul_f32_e32 v67, v71, v77
	v_cvt_pk_bf16_f32 v66, v66, v67
	ds_write_b32 v70, v66 offset:128
	v_mul_f32_e32 v66, v68, v76
	v_mul_f32_e32 v67, v72, v77
	v_cvt_pk_bf16_f32 v66, v66, v67
	ds_write_b32 v70, v66 offset:256
	v_mul_f32_e32 v66, v69, v76
	v_mov_b32_e32 v75, 1.0
	v_mul_f32_e32 v67, v73, v77
	v_cvt_pk_bf16_f32 v66, v66, v67
	ds_write_b32 v70, v66 offset:384
	s_and_saveexec_b64 s[34:35], vcc
	s_cbranch_execz .Lmy_w130
	v_mov_b32_e32 v103, v93
	v_lshl_add_u64 v[66:67], v[100:101], 0, v[102:103]
	v_mov_b32_e32 v74, v186
	v_mov_b32_e32 v75, v187
.Lmy_w130:
	s_or_b64 exec, exec, s[34:35]
	s_waitcnt vmcnt(0)
	v_mul_f32_e32 v58, v58, v74
	v_mul_f32_e32 v62, v62, v75
	v_cvt_pk_bf16_f32 v58, v58, v62
	v_add_u32_e32 v62, v113, v110
	ds_write_b32 v62, v58
	v_mul_f32_e32 v58, v59, v74
	v_mul_f32_e32 v59, v63, v75
	v_cvt_pk_bf16_f32 v58, v58, v59
	ds_write_b32 v62, v58 offset:128
	v_mul_f32_e32 v58, v60, v74
	v_mul_f32_e32 v59, v64, v75
	v_cvt_pk_bf16_f32 v58, v58, v59
	ds_write_b32 v62, v58 offset:256
	v_mul_f32_e32 v58, v61, v74
	v_mul_f32_e32 v59, v65, v75
	v_cvt_pk_bf16_f32 v58, v58, v59
	ds_write_b32 v62, v58 offset:384
	v_mov_b32_e32 v58, 1.0
	v_mov_b32_e32 v60, 1.0
	v_mov_b32_e32 v61, 1.0
	s_and_saveexec_b64 s[34:35], vcc
	s_cbranch_execz .Lmy_w132
	v_mov_b32_e32 v103, v93
	v_lshl_add_u64 v[60:61], v[100:101], 0, v[102:103]
	v_mov_b32_e32 v60, v188
	v_mov_b32_e32 v61, v189
.Lmy_w132:
	s_or_b64 exec, exec, s[34:35]
	s_waitcnt vmcnt(0)
	v_mul_f32_e32 v50, v50, v60
	v_mul_f32_e32 v54, v54, v61
	v_cvt_pk_bf16_f32 v50, v50, v54
	v_add_u32_e32 v54, v114, v110
	ds_write_b32 v54, v50
	v_mul_f32_e32 v50, v51, v60
	v_mul_f32_e32 v51, v55, v61
	v_cvt_pk_bf16_f32 v50, v50, v51
	ds_write_b32 v54, v50 offset:128
	v_mul_f32_e32 v50, v52, v60
	v_mul_f32_e32 v51, v56, v61
	v_cvt_pk_bf16_f32 v50, v50, v51
	ds_write_b32 v54, v50 offset:256
	v_mul_f32_e32 v50, v53, v60
	v_mov_b32_e32 v59, 1.0
	v_mul_f32_e32 v51, v57, v61
	v_cvt_pk_bf16_f32 v50, v50, v51
	ds_write_b32 v54, v50 offset:384
	s_and_saveexec_b64 s[34:35], vcc
	s_cbranch_execz .Lmy_w134
	v_mov_b32_e32 v103, v93
	v_lshl_add_u64 v[50:51], v[100:101], 0, v[102:103]
	v_mov_b32_e32 v58, v190
	v_mov_b32_e32 v59, v191
.Lmy_w134:
	s_or_b64 exec, exec, s[34:35]
	s_waitcnt vmcnt(0)
	v_mul_f32_e32 v42, v42, v58
	v_mul_f32_e32 v46, v46, v59
	v_cvt_pk_bf16_f32 v42, v42, v46
	v_add_u32_e32 v46, v115, v110
	ds_write_b32 v46, v42
	v_mul_f32_e32 v42, v43, v58
	v_mul_f32_e32 v43, v47, v59
	v_cvt_pk_bf16_f32 v42, v42, v43
	ds_write_b32 v46, v42 offset:128
	v_mul_f32_e32 v42, v44, v58
	v_mul_f32_e32 v43, v48, v59
	v_cvt_pk_bf16_f32 v42, v42, v43
	ds_write_b32 v46, v42 offset:256
	v_mul_f32_e32 v42, v45, v58
	v_mul_f32_e32 v43, v49, v59
	v_cvt_pk_bf16_f32 v42, v42, v43
	ds_write_b32 v46, v42 offset:384
	v_mov_b32_e32 v42, 1.0
	v_mov_b32_e32 v44, 1.0
	v_mov_b32_e32 v45, 1.0
	s_and_saveexec_b64 s[34:35], vcc
	s_cbranch_execz .Lmy_w136
	v_mov_b32_e32 v103, v93
	v_lshl_add_u64 v[44:45], v[100:101], 0, v[102:103]
	v_mov_b32_e32 v44, v192
	v_mov_b32_e32 v45, v193
.Lmy_w136:
	s_or_b64 exec, exec, s[34:35]
	s_waitcnt vmcnt(0)
	v_mul_f32_e32 v34, v34, v44
	v_mul_f32_e32 v38, v38, v45
	v_cvt_pk_bf16_f32 v34, v34, v38
	v_add_u32_e32 v38, v116, v110
	ds_write_b32 v38, v34
	v_mul_f32_e32 v34, v35, v44
	v_mul_f32_e32 v35, v39, v45
	v_cvt_pk_bf16_f32 v34, v34, v35
	ds_write_b32 v38, v34 offset:128
	v_mul_f32_e32 v34, v36, v44
	v_mul_f32_e32 v35, v40, v45
	v_cvt_pk_bf16_f32 v34, v34, v35
	ds_write_b32 v38, v34 offset:256
	v_mul_f32_e32 v34, v37, v44
	v_mov_b32_e32 v43, 1.0
	v_mul_f32_e32 v35, v41, v45
	v_cvt_pk_bf16_f32 v34, v34, v35
	ds_write_b32 v38, v34 offset:384
	s_and_saveexec_b64 s[34:35], vcc
	s_cbranch_execz .Lmy_w138
	v_mov_b32_e32 v103, v93
	v_lshl_add_u64 v[34:35], v[100:101], 0, v[102:103]
	v_mov_b32_e32 v42, v194
	v_mov_b32_e32 v43, v195

; #define LAS __attribute__((address_space(3)))
; __device__ __forceinline__ void p0_transpose_item(const float* W, int K, int N, const float* gain, const float* gain2  , bf16_t* WT, LAS unsigned* scr, int item, int lane) {
;     const int nblk = N / 64, kb = item / nblk, nb = item % nblk, k0 = 64 * kb, n0 = 64 * nb;
;     if (gain2 && k0 >= 1024) gain = gain2 - 1024;
;     const int n4 = lane & 15, kq = lane >> 4;
;     f32x4 r0[8], r1[8];
;     const float* src = W + (size_t)(k0 + 2 * kq) * N + n0 + 4 * n4;
; #pragma unroll
;     for (int j = 0; j < 8; ++j) { r0[j] = __builtin_nontemporal_load((const f32x4*)(src + (size_t)(8 * j) * N)); r1[j] = __builtin_nontemporal_load((const f32x4*)(src + (size_t)(8 * j + 1) * N)); }
; #pragma unroll
;     for (int j = 0; j < 8; ++j) {
;         float g0 = 1.f, g1 = 1.f; if (gain) { g0 = gain[k0 + 8 * j + 2 * kq]; g1 = gain[k0 + 8 * j + 2 * kq + 1]; }
; __device__ __forceinline__ void p0_prologue(const Params& p, LAS unsigned char* lds, int tid) {
;     ...
;         if (r < I_UP) { p0_transpose_item(p.in[21] + (size_t)l * DM * DFF, DM, DFF, p.in[20] + l * DM, nullptr, (bf16_t*)(wl + LO_WUP), scr, r, lane); continue; } r -= I_UP;
.Lmy_w145:
	s_andn2_saveexec_b64 s[28:29], s[0:1]
	s_cbranch_execz .Lmy_w163
	v_add_u32_e32 v26, 0xfb00, v26
	v_lshrrev_b32_e32 v26, 1, v26
	v_readlane_b32 s40, v253, 18
	v_and_b32_e32 v109, 0x7fc0, v26
	v_lshlrev_b32_e32 v26, 6, v27
	v_lshlrev_b64 v[28:29], 26, v[100:101]
	v_readlane_b32 s50, v253, 28
	v_readlane_b32 s51, v253, 29
	v_sub_u32_e32 v26, v134, v26
	v_or_b32_e32 v102, v109, v91
	v_lshl_add_u64 v[28:29], s[50:51], 0, v[28:29]
	v_and_b32_e32 v108, 0x1fc0, v26
	v_lshlrev_b32_e32 v26, 15, v102
	v_mov_b32_e32 v27, v93
	v_lshl_add_u64 v[26:27], v[28:29], 0, v[26:27]
	v_lshlrev_b32_e32 v28, 2, v108
	v_mov_b32_e32 v29, v93
	v_lshl_add_u64 v[26:27], v[26:27], 0, v[28:29]
	v_lshl_add_u64 v[26:27], v[26:27], 0, v[92:93]
	s_mov_b32 s0, 0x8000
	v_add_co_u32_e32 v28, vcc, s0, v26
	v_lshlrev_b32_e32 v100, 11, v100
	s_nop 0
	v_addc_co_u32_e32 v29, vcc, 0, v27, vcc
	global_load_dwordx4 v[82:85], v[26:27], off nt
	global_load_dwordx4 v[86:89], v[28:29], off nt
	v_add_co_u32_e32 v28, vcc, s78, v26
	v_readlane_b32 s48, v253, 26
	s_nop 0
	v_addc_co_u32_e32 v29, vcc, 0, v27, vcc
	v_add_co_u32_e32 v30, vcc, s86, v26
	v_readlane_b32 s49, v253, 27
	s_nop 0
	v_addc_co_u32_e32 v31, vcc, 0, v27, vcc
	global_load_dwordx4 v[74:77], v[28:29], off nt
	global_load_dwordx4 v[78:81], v[30:31], off nt
	v_add_co_u32_e32 v28, vcc, s87, v26
	v_ashrrev_i32_e32 v101, 31, v100
	s_nop 0
	v_addc_co_u32_e32 v29, vcc, 0, v27, vcc
	v_add_co_u32_e32 v30, vcc, s88, v26
	v_cndmask_b32_e64 v103, 0, 1, s[8:9]
	s_nop 0
	v_addc_co_u32_e32 v31, vcc, 0, v27, vcc
	global_load_dwordx4 v[66:69], v[28:29], off nt
	global_load_dwordx4 v[70:73], v[30:31], off nt
	v_add_co_u32_e32 v28, vcc, s89, v26
	v_lshl_add_u64 v[100:101], v[100:101], 2, s[48:49]
	s_nop 0
	v_addc_co_u32_e32 v29, vcc, 0, v27, vcc
	v_add_co_u32_e32 v30, vcc, s56, v26
	v_mov_b32_e32 v104, 1.0
	s_nop 0
	v_addc_co_u32_e32 v31, vcc, 0, v27, vcc
	global_load_dwordx4 v[58:61], v[28:29], off nt
	global_load_dwordx4 v[62:65], v[30:31], off nt
	v_add_co_u32_e32 v28, vcc, s57, v26
	v_cmp_ne_u32_e64 s[0:1], 1, v103
	s_nop 0
	v_addc_co_u32_e32 v29, vcc, 0, v27, vcc
	v_add_co_u32_e32 v30, vcc, s58, v26
	v_lshlrev_b32_e32 v102, 2, v102
	s_nop 0
	v_addc_co_u32_e32 v31, vcc, 0, v27, vcc
	global_load_dwordx4 v[50:53], v[28:29], off nt
	s_waitcnt lgkmcnt(0)
	global_load_dwordx4 v[54:57], v[30:31], off nt
	v_add_co_u32_e32 v28, vcc, s59, v26
	v_mov_b32_e32 v106, 1.0
	s_nop 0
	v_addc_co_u32_e32 v29, vcc, 0, v27, vcc
	v_add_co_u32_e32 v30, vcc, s60, v26
	v_mov_b32_e32 v107, 1.0
	s_nop 0
	v_addc_co_u32_e32 v31, vcc, 0, v27, vcc
	global_load_dwordx4 v[42:45], v[28:29], off nt
	global_load_dwordx4 v[46:49], v[30:31], off nt
	v_add_co_u32_e32 v28, vcc, s61, v26
	v_readlane_b32 s41, v253, 19
	s_nop 0
	v_addc_co_u32_e32 v29, vcc, 0, v27, vcc
	v_add_co_u32_e32 v30, vcc, 0x188000, v26
	v_readlane_b32 s42, v253, 20
	s_nop 0
	v_addc_co_u32_e32 v31, vcc, 0, v27, vcc
	global_load_dwordx4 v[34:37], v[28:29], off nt
	global_load_dwordx4 v[38:41], v[30:31], off nt
	v_add_co_u32_e32 v28, vcc, 0x1c0000, v26
	v_readlane_b32 s43, v253, 21
	s_nop 0
	v_addc_co_u32_e32 v29, vcc, 0, v27, vcc
	v_add_co_u32_e32 v30, vcc, 0x1c8000, v26
	v_readlane_b32 s44, v253, 22
	s_nop 0
	v_addc_co_u32_e32 v31, vcc, 0, v27, vcc
	global_load_dwordx4 v[26:29], v[28:29], off nt
	s_nop 0
	global_load_dwordx4 v[30:33], v[30:31], off nt
	s_andn2_b64 vcc, exec, s[8:9]
	v_readlane_b32 s45, v253, 23
	v_readlane_b32 s46, v253, 24
	v_readlane_b32 s47, v253, 25
	v_readlane_b32 s52, v253, 30
	v_readlane_b32 s53, v253, 31
	v_readlane_b32 s54, v253, 32
	v_readlane_b32 s55, v253, 33
	s_cbranch_vccnz .Lmy_w148
	v_mov_b32_e32 v103, v93
	v_lshl_add_u64 v[106:107], v[100:101], 0, v[102:103]
	global_load_dwordx2 v[182:183], v[106:107], off offset:32
	global_load_dwordx2 v[184:185], v[106:107], off offset:64
	global_load_dwordx2 v[186:187], v[106:107], off offset:96
	global_load_dwordx2 v[188:189], v[106:107], off offset:128
	global_load_dwordx2 v[190:191], v[106:107], off offset:160
	global_load_dwordx2 v[192:193], v[106:107], off offset:192
	global_load_dwordx2 v[194:195], v[106:107], off offset:224
	global_load_dwordx2 v[106:107], v[106:107], off
.Lmy_w148:
	s_waitcnt vmcnt(0)
	v_mul_f32_e32 v82, v82, v106
	v_mul_f32_e32 v86, v86, v107
	v_cvt_pk_bf16_f32 v82, v82, v86
	v_add_u32_e32 v86, v95, v110
	ds_write_b32 v86, v82
	v_mul_f32_e32 v82, v83, v106
	v_mul_f32_e32 v83, v87, v107
	v_cvt_pk_bf16_f32 v82, v82, v83
	ds_write_b32 v86, v82 offset:128
	v_mul_f32_e32 v82, v84, v106
	v_mul_f32_e32 v83, v88, v107
	v_cvt_pk_bf16_f32 v82, v82, v83
	ds_write_b32 v86, v82 offset:256
	v_mul_f32_e32 v82, v85, v106
	s_and_b64 vcc, exec, s[0:1]
	v_mov_b32_e32 v105, 1.0
	v_mul_f32_e32 v83, v89, v107
	v_cvt_pk_bf16_f32 v82, v82, v83
	ds_write_b32 v86, v82 offset:384
	s_cbranch_vccnz .Lmy_w150
	v_mov_b32_e32 v103, v93
	v_lshl_add_u64 v[82:83], v[100:101], 0, v[102:103]
	v_mov_b32_e32 v104, v182
	v_mov_b32_e32 v105, v183
; __device__ __forceinline__ unsigned pk2(float lo, float hi) { unsigned r; asm volatile("v_cvt_pk_bf16_f32 %0, %1, %2" : "=v"(r) : "v"(lo), "v"(hi)); return r; }
; __device__ __forceinline__ void p0_transpose_item(const float* W, int K, int N, const float* gain, const float* gain2  , bf16_t* WT, LAS unsigned* scr, int item, int lane) {
;     ...
;     for (int j = 0; j < 8; ++j) {
;         float g0 = 1.f, g1 = 1.f; if (gain) { g0 = gain[k0 + 8 * j + 2 * kq]; g1 = gain[k0 + 8 * j + 2 * kq + 1]; }
; #pragma unroll
;         for (int i = 0; i < 4; ++i) scr[(4 * n4 + i) * 32 + (((j ^ (n4 & 7)) << 2) | kq)] = pk2(r0[j][i] * g0, r1[j][i] * g1);
;     }
.Lmy_w150:
	s_waitcnt vmcnt(0)
	v_mul_f32_e32 v74, v74, v104
	v_mul_f32_e32 v78, v78, v105
	v_cvt_pk_bf16_f32 v74, v74, v78
	v_add_u32_e32 v78, v111, v110
	ds_write_b32 v78, v74
	v_mul_f32_e32 v74, v75, v104
	v_mul_f32_e32 v75, v79, v105
	v_cvt_pk_bf16_f32 v74, v74, v75
	ds_write_b32 v78, v74 offset:128
	v_mul_f32_e32 v74, v76, v104
	v_mul_f32_e32 v75, v80, v105
	v_cvt_pk_bf16_f32 v74, v74, v75
	ds_write_b32 v78, v74 offset:256
	v_mul_f32_e32 v74, v77, v104
	v_mul_f32_e32 v75, v81, v105
	v_cvt_pk_bf16_f32 v74, v74, v75
	ds_write_b32 v78, v74 offset:384
	v_mov_b32_e32 v74, 1.0
	s_and_b64 vcc, exec, s[0:1]
	v_mov_b32_e32 v76, 1.0
	v_mov_b32_e32 v77, 1.0
	s_cbranch_vccnz .Lmy_w152
	v_mov_b32_e32 v103, v93
	v_lshl_add_u64 v[76:77], v[100:101], 0, v[102:103]
	v_mov_b32_e32 v76, v184
	v_mov_b32_e32 v77, v185
.Lmy_w152:
	s_waitcnt vmcnt(0)
	v_mul_f32_e32 v66, v66, v76
	v_mul_f32_e32 v70, v70, v77
	v_cvt_pk_bf16_f32 v66, v66, v70
	v_add_u32_e32 v70, v112, v110
	ds_write_b32 v70, v66
	v_mul_f32_e32 v66, v67, v76
	v_mul_f32_e32 v67, v71, v77
	v_cvt_pk_bf16_f32 v66, v66, v67
	ds_write_b32 v70, v66 offset:128
	v_mul_f32_e32 v66, v68, v76
	v_mul_f32_e32 v67, v72, v77
	v_cvt_pk_bf16_f32 v66, v66, v67
	ds_write_b32 v70, v66 offset:256
	v_mul_f32_e32 v66, v69, v76
	s_and_b64 vcc, exec, s[0:1]
	v_mov_b32_e32 v75, 1.0
	v_mul_f32_e32 v67, v73, v77
	v_cvt_pk_bf16_f32 v66, v66, v67
	ds_write_b32 v70, v66 offset:384
	s_cbranch_vccnz .Lmy_w154
	v_mov_b32_e32 v103, v93
	v_lshl_add_u64 v[66:67], v[100:101], 0, v[102:103]
	v_mov_b32_e32 v74, v186
	v_mov_b32_e32 v75, v187
.Lmy_w154:
	s_waitcnt vmcnt(0)
	v_mul_f32_e32 v58, v58, v74
	v_mul_f32_e32 v62, v62, v75
	v_cvt_pk_bf16_f32 v58, v58, v62
	v_add_u32_e32 v62, v113, v110
	ds_write_b32 v62, v58
	v_mul_f32_e32 v58, v59, v74
	v_mul_f32_e32 v59, v63, v75
	v_cvt_pk_bf16_f32 v58, v58, v59
	ds_write_b32 v62, v58 offset:128
	v_mul_f32_e32 v58, v60, v74
	v_mul_f32_e32 v59, v64, v75
	v_cvt_pk_bf16_f32 v58, v58, v59
	ds_write_b32 v62, v58 offset:256
	v_mul_f32_e32 v58, v61, v74
	v_mul_f32_e32 v59, v65, v75
	v_cvt_pk_bf16_f32 v58, v58, v59
	ds_write_b32 v62, v58 offset:384
	v_mov_b32_e32 v58, 1.0
	s_and_b64 vcc, exec, s[0:1]
	v_mov_b32_e32 v60, 1.0
	v_mov_b32_e32 v61, 1.0
	s_cbranch_vccnz .Lmy_w156
	v_mov_b32_e32 v103, v93
	v_lshl_add_u64 v[60:61], v[100:101], 0, v[102:103]
	v_mov_b32_e32 v60, v188
	v_mov_b32_e32 v61, v189
.Lmy_w156:
	s_waitcnt vmcnt(0)
	v_mul_f32_e32 v50, v50, v60
	v_mul_f32_e32 v54, v54, v61
	v_cvt_pk_bf16_f32 v50, v50, v54
	v_add_u32_e32 v54, v114, v110
	ds_write_b32 v54, v50
	v_mul_f32_e32 v50, v51, v60
	v_mul_f32_e32 v51, v55, v61
	v_cvt_pk_bf16_f32 v50, v50, v51
	ds_write_b32 v54, v50 offset:128
	v_mul_f32_e32 v50, v52, v60
	v_mul_f32_e32 v51, v56, v61
	v_cvt_pk_bf16_f32 v50, v50, v51
	ds_write_b32 v54, v50 offset:256
	v_mul_f32_e32 v50, v53, v60
	s_and_b64 vcc, exec, s[0:1]
	v_mov_b32_e32 v59, 1.0
	v_mul_f32_e32 v51, v57, v61
	v_cvt_pk_bf16_f32 v50, v50, v51
	ds_write_b32 v54, v50 offset:384
	s_cbranch_vccnz .Lmy_w158
	v_mov_b32_e32 v103, v93
	v_lshl_add_u64 v[50:51], v[100:101], 0, v[102:103]
	v_mov_b32_e32 v58, v190
	v_mov_b32_e32 v59, v191
.Lmy_w158:
	s_waitcnt vmcnt(0)
	v_mul_f32_e32 v42, v42, v58
	v_mul_f32_e32 v46, v46, v59
	v_cvt_pk_bf16_f32 v42, v42, v46
	v_add_u32_e32 v46, v115, v110
	ds_write_b32 v46, v42
	v_mul_f32_e32 v42, v43, v58
	v_mul_f32_e32 v43, v47, v59
	v_cvt_pk_bf16_f32 v42, v42, v43
	ds_write_b32 v46, v42 offset:128
	v_mul_f32_e32 v42, v44, v58
	v_mul_f32_e32 v43, v48, v59
	v_cvt_pk_bf16_f32 v42, v42, v43
	ds_write_b32 v46, v42 offset:256
	v_mul_f32_e32 v42, v45, v58
	v_mul_f32_e32 v43, v49, v59
	v_cvt_pk_bf16_f32 v42, v42, v43
	ds_write_b32 v46, v42 offset:384
	v_mov_b32_e32 v42, 1.0
	s_and_b64 vcc, exec, s[0:1]
	v_mov_b32_e32 v44, 1.0
	v_mov_b32_e32 v45, 1.0
	s_cbranch_vccnz .Lmy_w160
	v_mov_b32_e32 v103, v93
	v_lshl_add_u64 v[44:45], v[100:101], 0, v[102:103]
	v_mov_b32_e32 v44, v192
	v_mov_b32_e32 v45, v193
.Lmy_w160:
	s_waitcnt vmcnt(0)
	v_mul_f32_e32 v34, v34, v44
	v_mul_f32_e32 v38, v38, v45
	v_cvt_pk_bf16_f32 v34, v34, v38
	v_add_u32_e32 v38, v116, v110
	ds_write_b32 v38, v34
	v_mul_f32_e32 v34, v35, v44
	v_mul_f32_e32 v35, v39, v45
	v_cvt_pk_bf16_f32 v34, v34, v35
	ds_write_b32 v38, v34 offset:128
	v_mul_f32_e32 v34, v36, v44
	v_mul_f32_e32 v35, v40, v45
	v_cvt_pk_bf16_f32 v34, v34, v35
	ds_write_b32 v38, v34 offset:256
	v_mul_f32_e32 v34, v37, v44
	s_and_b64 vcc, exec, s[0:1]
	v_mov_b32_e32 v43, 1.0
	v_mul_f32_e32 v35, v41, v45
	v_cvt_pk_bf16_f32 v34, v34, v35
	ds_write_b32 v38, v34 offset:384
	s_cbranch_vccnz .Lmy_w162
	v_mov_b32_e32 v103, v93
	v_lshl_add_u64 v[34:35], v[100:101], 0, v[102:103]
	v_mov_b32_e32 v42, v194
	v_mov_b32_e32 v43, v195

; #define LAS __attribute__((address_space(3)))
; __device__ __forceinline__ void p0_transpose_item(const float* W, int K, int N, const float* gain, const float* gain2  , bf16_t* WT, LAS unsigned* scr, int item, int lane) {
;     const int nblk = N / 64, kb = item / nblk, nb = item % nblk, k0 = 64 * kb, n0 = 64 * nb;
;     if (gain2 && k0 >= 1024) gain = gain2 - 1024;
;     const int n4 = lane & 15, kq = lane >> 4;
;     f32x4 r0[8], r1[8];
;     const float* src = W + (size_t)(k0 + 2 * kq) * N + n0 + 4 * n4;
; #pragma unroll
;     for (int j = 0; j < 8; ++j) { r0[j] = __builtin_nontemporal_load((const f32x4*)(src + (size_t)(8 * j) * N)); r1[j] = __builtin_nontemporal_load((const f32x4*)(src + (size_t)(8 * j + 1) * N)); }
; #pragma unroll
;     for (int j = 0; j < 8; ++j) {
;         float g0 = 1.f, g1 = 1.f; if (gain) { g0 = gain[k0 + 8 * j + 2 * kq]; g1 = gain[k0 + 8 * j + 2 * kq + 1]; }
; __device__ __forceinline__ void p0_prologue(const Params& p, LAS unsigned char* lds, int tid) {
;     ...
;         if (r < I_IN) { p0_transpose_item(p.in[3] + (size_t)l * DM * INW, DM, INW, p.in[2] + l * DM, nullptr, (bf16_t*)(wl + LO_WIN), scr, r, lane); continue; } r -= I_IN;
.Lmy_w164:
	s_andn2_saveexec_b64 s[26:27], s[26:27]
	s_cbranch_execz .Lmy_w117
	v_readlane_b32 s40, v253, 2
	v_mul_i32_i24_e32 v27, 0x6667, v26
	v_readlane_b32 s41, v253, 3
	v_readlane_b32 s42, v253, 4
	v_readlane_b32 s43, v253, 5
	v_readlane_b32 s44, v253, 6
	v_readlane_b32 s45, v253, 7
	v_lshrrev_b32_e32 v30, 31, v27
	v_ashrrev_i32_e32 v27, 20, v27
	v_readlane_b32 s46, v253, 8
	v_readlane_b32 s47, v253, 9
	s_mov_b64 s[40:41], s[44:45]
	v_add_u16_e32 v27, v27, v30
	s_mov_b64 s[42:43], s[46:47]
	v_mul_lo_u16_e32 v30, 40, v27
	v_lshlrev_b32_sdwa v104, v138, sext(v27) dst_sel:DWORD dst_unused:UNUSED_PAD src0_sel:DWORD src1_sel:WORD_0
	v_mov_b64_e32 v[28:29], s[42:43]
	v_sub_u16_e32 v26, v26, v30
	v_or_b32_e32 v108, v104, v91
	v_mad_i64_i32 v[28:29], s[0:1], v100, s64, v[28:29]
	v_lshlrev_b32_sdwa v102, v138, sext(v26) dst_sel:DWORD dst_unused:UNUSED_PAD src0_sel:DWORD src1_sel:WORD_0
	v_mul_hi_i32_i24_e32 v27, 0x2800, v108
	v_mul_i32_i24_e32 v26, 0x2800, v108
	v_lshl_add_u64 v[26:27], v[28:29], 0, v[26:27]
	v_ashrrev_i32_e32 v103, 31, v102
	v_lshl_add_u64 v[26:27], v[102:103], 2, v[26:27]
	v_lshl_add_u64 v[26:27], v[26:27], 0, v[92:93]
	v_add_co_u32_e32 v28, vcc, s37, v26
	s_mov_b32 s0, 0x28000
	s_nop 0
	v_addc_co_u32_e32 v29, vcc, 0, v27, vcc
	global_load_dwordx4 v[82:85], v[26:27], off nt
	global_load_dwordx4 v[86:89], v[28:29], off offset:2048 nt
	v_add_co_u32_e32 v28, vcc, s65, v26
	v_lshlrev_b32_e32 v100, 11, v100
	s_nop 0
	v_addc_co_u32_e32 v29, vcc, 0, v27, vcc
	v_add_co_u32_e32 v30, vcc, s66, v26
	v_ashrrev_i32_e32 v101, 31, v100
	s_nop 0
	v_addc_co_u32_e32 v31, vcc, 0, v27, vcc
	global_load_dwordx4 v[74:77], v[28:29], off nt
	global_load_dwordx4 v[78:81], v[30:31], off offset:2048 nt
	v_add_co_u32_e32 v28, vcc, s0, v26
	v_lshl_add_u64 v[100:101], v[100:101], 2, s[40:41]
	s_nop 0
	v_addc_co_u32_e32 v29, vcc, 0, v27, vcc
	v_add_co_u32_e32 v30, vcc, s67, v26
	v_ashrrev_i32_e32 v109, 31, v108
	s_nop 0
	v_addc_co_u32_e32 v31, vcc, 0, v27, vcc
	global_load_dwordx4 v[66:69], v[28:29], off nt
	global_load_dwordx4 v[70:73], v[30:31], off offset:2048 nt
	v_add_co_u32_e32 v28, vcc, s68, v26
	v_cndmask_b32_e64 v103, 0, 1, s[12:13]
	s_nop 0
	v_addc_co_u32_e32 v29, vcc, 0, v27, vcc
	v_add_co_u32_e32 v30, vcc, s69, v26
	v_mov_b32_e32 v106, 1.0
	s_nop 0
	v_addc_co_u32_e32 v31, vcc, 0, v27, vcc
	global_load_dwordx4 v[58:61], v[28:29], off nt
	global_load_dwordx4 v[62:65], v[30:31], off offset:2048 nt
	v_add_co_u32_e32 v28, vcc, s80, v26
	v_cmp_ne_u32_e64 s[0:1], 1, v103
	s_nop 0
	v_addc_co_u32_e32 v29, vcc, 0, v27, vcc
	v_add_co_u32_e32 v30, vcc, s81, v26
	v_lshl_add_u64 v[100:101], v[108:109], 2, v[100:101]
	s_nop 0
	v_addc_co_u32_e32 v31, vcc, 0, v27, vcc
	global_load_dwordx4 v[50:53], v[28:29], off nt
	s_waitcnt lgkmcnt(0)
	global_load_dwordx4 v[54:57], v[30:31], off offset:2048 nt
	v_add_co_u32_e32 v28, vcc, s70, v26
	v_mov_b32_e32 v108, 1.0
	s_nop 0
	v_addc_co_u32_e32 v29, vcc, 0, v27, vcc
	v_add_co_u32_e32 v30, vcc, s71, v26
	v_mov_b32_e32 v109, 1.0
	s_nop 0
	v_addc_co_u32_e32 v31, vcc, 0, v27, vcc
	global_load_dwordx4 v[42:45], v[28:29], off nt
	global_load_dwordx4 v[46:49], v[30:31], off offset:2048 nt
	v_add_co_u32_e32 v28, vcc, s72, v26
	v_readlane_b32 s48, v253, 10
	s_nop 0
	v_addc_co_u32_e32 v29, vcc, 0, v27, vcc
	v_add_co_u32_e32 v30, vcc, 0x7a000, v26
	v_readlane_b32 s49, v253, 11
	s_nop 0
	v_addc_co_u32_e32 v31, vcc, 0, v27, vcc
	global_load_dwordx4 v[34:37], v[28:29], off nt
	global_load_dwordx4 v[38:41], v[30:31], off offset:2048 nt
	v_add_co_u32_e32 v28, vcc, 0x8c000, v26
	v_readlane_b32 s50, v253, 12
	s_nop 0
	v_addc_co_u32_e32 v29, vcc, 0, v27, vcc
	v_add_co_u32_e32 v30, vcc, 0x8e000, v26
	v_readlane_b32 s51, v253, 13
	s_nop 0
	v_addc_co_u32_e32 v31, vcc, 0, v27, vcc
	global_load_dwordx4 v[26:29], v[28:29], off nt
	s_nop 0
	global_load_dwordx4 v[30:33], v[30:31], off offset:2048 nt
	s_andn2_b64 vcc, exec, s[12:13]
	v_readlane_b32 s52, v253, 14
	v_readlane_b32 s53, v253, 15
	v_readlane_b32 s54, v253, 16
	v_readlane_b32 s55, v253, 17
	s_cbranch_vccnz .Lmy_w167
	global_load_dwordx2 v[182:183], v[100:101], off offset:32
	global_load_dwordx2 v[184:185], v[100:101], off offset:64
	global_load_dwordx2 v[186:187], v[100:101], off offset:96
	global_load_dwordx2 v[188:189], v[100:101], off offset:128
	global_load_dwordx2 v[190:191], v[100:101], off offset:160
	global_load_dwordx2 v[192:193], v[100:101], off offset:192
	global_load_dwordx2 v[194:195], v[100:101], off offset:224
	global_load_dwordx2 v[108:109], v[100:101], off
; __device__ __forceinline__ unsigned pk2(float lo, float hi) { unsigned r; asm volatile("v_cvt_pk_bf16_f32 %0, %1, %2" : "=v"(r) : "v"(lo), "v"(hi)); return r; }
; __device__ __forceinline__ void p0_transpose_item(const float* W, int K, int N, const float* gain, const float* gain2  , bf16_t* WT, LAS unsigned* scr, int item, int lane) {
;     ...
;     for (int j = 0; j < 8; ++j) {
;         float g0 = 1.f, g1 = 1.f; if (gain) { g0 = gain[k0 + 8 * j + 2 * kq]; g1 = gain[k0 + 8 * j + 2 * kq + 1]; }
; #pragma unroll
;         for (int i = 0; i < 4; ++i) scr[(4 * n4 + i) * 32 + (((j ^ (n4 & 7)) << 2) | kq)] = pk2(r0[j][i] * g0, r1[j][i] * g1);
;     }
.Lmy_w167:
	s_waitcnt vmcnt(0)
	v_mul_f32_e32 v82, v82, v108
	v_mul_f32_e32 v86, v86, v109
	v_cvt_pk_bf16_f32 v82, v82, v86
	v_add_u32_e32 v86, v95, v110
	ds_write_b32 v86, v82
	v_mul_f32_e32 v82, v83, v108
	v_mul_f32_e32 v83, v87, v109
	v_cvt_pk_bf16_f32 v82, v82, v83
	ds_write_b32 v86, v82 offset:128
	v_mul_f32_e32 v82, v84, v108
	v_mul_f32_e32 v83, v88, v109
	v_cvt_pk_bf16_f32 v82, v82, v83
	ds_write_b32 v86, v82 offset:256
	v_mul_f32_e32 v82, v85, v108
	s_and_b64 vcc, exec, s[0:1]
	v_mov_b32_e32 v107, 1.0
	v_mul_f32_e32 v83, v89, v109
	v_cvt_pk_bf16_f32 v82, v82, v83
	ds_write_b32 v86, v82 offset:384
	s_cbranch_vccnz .Lmy_w169
	v_mov_b32_e32 v106, v182
	v_mov_b32_e32 v107, v183
.Lmy_w169:
	s_waitcnt vmcnt(0)
	v_mul_f32_e32 v74, v74, v106
	v_mul_f32_e32 v78, v78, v107
	v_cvt_pk_bf16_f32 v74, v74, v78
	v_add_u32_e32 v78, v111, v110
	ds_write_b32 v78, v74
	v_mul_f32_e32 v74, v75, v106
	v_mul_f32_e32 v75, v79, v107
	v_cvt_pk_bf16_f32 v74, v74, v75
	ds_write_b32 v78, v74 offset:128
	v_mul_f32_e32 v74, v76, v106
	v_mul_f32_e32 v75, v80, v107
	v_cvt_pk_bf16_f32 v74, v74, v75
	ds_write_b32 v78, v74 offset:256
	v_mul_f32_e32 v74, v77, v106
	v_mul_f32_e32 v75, v81, v107
	v_cvt_pk_bf16_f32 v74, v74, v75
	ds_write_b32 v78, v74 offset:384
	v_mov_b32_e32 v74, 1.0
	s_and_b64 vcc, exec, s[0:1]
	v_mov_b32_e32 v76, 1.0
	v_mov_b32_e32 v77, 1.0
	s_cbranch_vccnz .Lmy_w171
	v_mov_b32_e32 v76, v184
	v_mov_b32_e32 v77, v185
.Lmy_w171:
	s_waitcnt vmcnt(0)
	v_mul_f32_e32 v66, v66, v76
	v_mul_f32_e32 v70, v70, v77
	v_cvt_pk_bf16_f32 v66, v66, v70
	v_add_u32_e32 v70, v112, v110
	ds_write_b32 v70, v66
	v_mul_f32_e32 v66, v67, v76
	v_mul_f32_e32 v67, v71, v77
	v_cvt_pk_bf16_f32 v66, v66, v67
	ds_write_b32 v70, v66 offset:128
	v_mul_f32_e32 v66, v68, v76
	v_mul_f32_e32 v67, v72, v77
	v_cvt_pk_bf16_f32 v66, v66, v67
	ds_write_b32 v70, v66 offset:256
	v_mul_f32_e32 v66, v69, v76
	s_and_b64 vcc, exec, s[0:1]
	v_mov_b32_e32 v75, 1.0
	v_mul_f32_e32 v67, v73, v77
	v_cvt_pk_bf16_f32 v66, v66, v67
	ds_write_b32 v70, v66 offset:384
	s_cbranch_vccnz .Lmy_w173
	v_mov_b32_e32 v74, v186
	v_mov_b32_e32 v75, v187
.Lmy_w173:
	s_waitcnt vmcnt(0)
	v_mul_f32_e32 v58, v58, v74
	v_mul_f32_e32 v62, v62, v75
	v_cvt_pk_bf16_f32 v58, v58, v62
	v_add_u32_e32 v62, v113, v110
	ds_write_b32 v62, v58
	v_mul_f32_e32 v58, v59, v74
	v_mul_f32_e32 v59, v63, v75
	v_cvt_pk_bf16_f32 v58, v58, v59
	ds_write_b32 v62, v58 offset:128
	v_mul_f32_e32 v58, v60, v74
	v_mul_f32_e32 v59, v64, v75
	v_cvt_pk_bf16_f32 v58, v58, v59
	ds_write_b32 v62, v58 offset:256
	v_mul_f32_e32 v58, v61, v74
	v_mul_f32_e32 v59, v65, v75
	v_cvt_pk_bf16_f32 v58, v58, v59
	ds_write_b32 v62, v58 offset:384
	v_mov_b32_e32 v58, 1.0
	s_and_b64 vcc, exec, s[0:1]
	v_mov_b32_e32 v60, 1.0
	v_mov_b32_e32 v61, 1.0
	s_cbranch_vccnz .Lmy_w175
	v_mov_b32_e32 v60, v188
	v_mov_b32_e32 v61, v189
.Lmy_w175:
	s_waitcnt vmcnt(0)
	v_mul_f32_e32 v50, v50, v60
	v_mul_f32_e32 v54, v54, v61
	v_cvt_pk_bf16_f32 v50, v50, v54
	v_add_u32_e32 v54, v114, v110
	ds_write_b32 v54, v50
	v_mul_f32_e32 v50, v51, v60
	v_mul_f32_e32 v51, v55, v61
	v_cvt_pk_bf16_f32 v50, v50, v51
	ds_write_b32 v54, v50 offset:128
	v_mul_f32_e32 v50, v52, v60
	v_mul_f32_e32 v51, v56, v61
	v_cvt_pk_bf16_f32 v50, v50, v51
	ds_write_b32 v54, v50 offset:256
	v_mul_f32_e32 v50, v53, v60
	s_and_b64 vcc, exec, s[0:1]
	v_mov_b32_e32 v59, 1.0
	v_mul_f32_e32 v51, v57, v61
	v_cvt_pk_bf16_f32 v50, v50, v51
	ds_write_b32 v54, v50 offset:384
	s_cbranch_vccnz .Lmy_w177
	v_mov_b32_e32 v58, v190
	v_mov_b32_e32 v59, v191
.Lmy_w177:
	s_waitcnt vmcnt(0)
	v_mul_f32_e32 v42, v42, v58
	v_mul_f32_e32 v46, v46, v59
	v_cvt_pk_bf16_f32 v42, v42, v46
	v_add_u32_e32 v46, v115, v110
	ds_write_b32 v46, v42
	v_mul_f32_e32 v42, v43, v58
	v_mul_f32_e32 v43, v47, v59
	v_cvt_pk_bf16_f32 v42, v42, v43
	ds_write_b32 v46, v42 offset:128
	v_mul_f32_e32 v42, v44, v58
	v_mul_f32_e32 v43, v48, v59
	v_cvt_pk_bf16_f32 v42, v42, v43
	ds_write_b32 v46, v42 offset:256
	v_mul_f32_e32 v42, v45, v58
	v_mul_f32_e32 v43, v49, v59
	v_cvt_pk_bf16_f32 v42, v42, v43
	ds_write_b32 v46, v42 offset:384
	v_mov_b32_e32 v42, 1.0
	s_and_b64 vcc, exec, s[0:1]
	v_mov_b32_e32 v44, 1.0
	v_mov_b32_e32 v45, 1.0
	s_cbranch_vccnz .Lmy_w179
	v_mov_b32_e32 v44, v192
	v_mov_b32_e32 v45, v193
.Lmy_w179:
	s_waitcnt vmcnt(0)
	v_mul_f32_e32 v34, v34, v44
	v_mul_f32_e32 v38, v38, v45
	v_cvt_pk_bf16_f32 v34, v34, v38
	v_add_u32_e32 v38, v116, v110
	ds_write_b32 v38, v34
	v_mul_f32_e32 v34, v35, v44
	v_mul_f32_e32 v35, v39, v45
	v_cvt_pk_bf16_f32 v34, v34, v35
	ds_write_b32 v38, v34 offset:128
	v_mul_f32_e32 v34, v36, v44
	v_mul_f32_e32 v35, v40, v45
	v_cvt_pk_bf16_f32 v34, v34, v35
	ds_write_b32 v38, v34 offset:256
	v_mul_f32_e32 v34, v37, v44
	s_and_b64 vcc, exec, s[0:1]
	v_mov_b32_e32 v43, 1.0
	v_mul_f32_e32 v35, v41, v45
	v_cvt_pk_bf16_f32 v34, v34, v35
	ds_write_b32 v38, v34 offset:384
	s_cbranch_vccnz .Lmy_w116
	v_mov_b32_e32 v42, v194
	v_mov_b32_e32 v43, v195
	s_branch .Lmy_w116
